# attention: normalised O tile transposed through LDS in f32 ([32][68]/wave, SSQ moved) instead of bf16: no O->bf16 pack before the LDS write and no unpack after the read (48 VALU fewer per iteration, o
# speedup vs baseline: 1.0003x; 1.0003x over previous
.LBB0_294:
	s_cmp_lt_i32 s80, 4
	s_cselect_b64 s[0:1], -1, 0
	s_cmp_gt_i32 s81, 3
	s_cselect_b64 s[4:5], -1, 0
	s_and_b64 s[0:1], s[0:1], s[4:5]
	s_andn2_b64 vcc, exec, s[0:1]
	s_cbranch_vccnz .LBB0_381
	v_lshrrev_b32_e32 v0, 5, v193
	s_cmpk_gt_i32 s2, 0x2ff
	v_and_b32_e32 v124, 31, v144
	v_mov_b32_e32 v127, 0
	v_lshlrev_b32_e32 v141, 3, v0
	v_lshlrev_b32_e32 v129, 2, v0
	s_cbranch_scc1 .LBB0_324
	v_and_b32_e32 v1, 7, v144
	v_lshl_add_u32 v3, v1, 4, 0
	v_lshlrev_b32_e32 v2, 3, v1
	v_add_u32_e32 v1, 0x200, v144
	v_lshrrev_b32_e32 v130, 3, v1
	v_or_b32_e32 v8, 0x400, v144
	v_lshrrev_b32_e32 v1, 5, v1
	s_add_u32 s50, s62, 0xc000000
	v_add_u32_e32 v10, 0x600, v144
	v_and_b32_e32 v6, 56, v1
	v_lshrrev_b32_e32 v1, 5, v8
	s_addc_u32 s51, s63, 0
	v_lshrrev_b32_e32 v132, 3, v8
	v_and_b32_e32 v8, 56, v1
	v_lshrrev_b32_e32 v1, 5, v10
	s_mul_i32 s6, s3, 0x2200
	v_lshrrev_b32_e32 v134, 3, v10
	v_and_b32_e32 v10, 0x78, v1
	s_add_u32 s93, s62, 0x1d00000
	v_lshlrev_b32_e32 v1, 3, v144
	s_addc_u32 s94, s63, 0
	s_add_i32 s6, s6, 0
	v_and_b32_e32 v12, 56, v1
	s_add_i32 s8, s6, 0x11400
	v_lshlrev_b32_e32 v126, 2, v12
	s_movk_i32 s92, 0x90
	s_waitcnt lgkmcnt(0)
	v_lshl_add_u64 v[138:139], s[12:13], 0, v[126:127]
	v_lshlrev_b32_e32 v18, 4, v0
	v_mov_b32_e32 v0, s8
	v_lshlrev_b32_e32 v126, 1, v12
	v_mul_u32_u24_e32 v19, 0x110, v124
	v_add_u32_e32 v19, v19, v0
	v_add_u32_e32 v20, s8, v126
	v_add_u32_e32 v20, v20, v126
	v_lshl_add_u64 v[0:1], s[62:63], 0, v[126:127]
	s_mov_b64 s[8:9], 0x4000000
	v_lshl_add_u64 v[142:143], v[0:1], 0, s[8:9]
	v_or_b32_e32 v0, 2, v129
	v_cmp_gt_u32_e64 s[12:13], v0, v124
	v_or_b32_e32 v0, 3, v129
	v_cmp_gt_u32_e64 s[14:15], v0, v124
	v_or_b32_e32 v0, 8, v129
	v_cmp_gt_u32_e64 s[16:17], v0, v124
	v_or_b32_e32 v0, 9, v129
	v_cmp_gt_u32_e64 s[18:19], v0, v124
	v_or_b32_e32 v0, 10, v129
	v_cmp_gt_u32_e64 s[20:21], v0, v124
	v_or_b32_e32 v0, 11, v129
	v_cmp_gt_u32_e64 s[22:23], v0, v124
	v_or_b32_e32 v0, 16, v129
	v_cmp_gt_u32_e64 s[24:25], v0, v124
	v_or_b32_e32 v0, 17, v129
	v_cmp_gt_u32_e64 s[26:27], v0, v124
	v_or_b32_e32 v0, 18, v129
	v_cmp_gt_u32_e64 s[28:29], v0, v124
	v_or_b32_e32 v0, 19, v129
	v_cmp_gt_u32_e64 s[30:31], v0, v124
	v_or_b32_e32 v0, 24, v129
	v_cmp_gt_u32_e64 s[34:35], v0, v124
	v_or_b32_e32 v0, 25, v129
	v_cmp_gt_u32_e64 s[36:37], v0, v124
	v_or_b32_e32 v0, 26, v129
	v_cmp_gt_u32_e64 s[38:39], v0, v124
	v_or_b32_e32 v0, 27, v129
	v_cmp_gt_u32_e64 s[40:41], v0, v124
	v_or_b32_e32 v0, 32, v193
	v_mul_u32_u24_e32 v22, 0x210, v0
	v_mbcnt_lo_u32_b32 v0, -1, 0
	v_mbcnt_hi_u32_b32 v0, -1, v0
	v_and_b32_e32 v24, 64, v0
	v_xor_b32_e32 v1, 32, v0
	v_add_u32_e32 v24, 64, v24
	v_cmp_lt_i32_e32 vcc, v1, v24
	s_mov_b64 s[56:57], 0xc048040
	v_lshrrev_b32_e32 v4, 5, v144
	v_cndmask_b32_e32 v0, v0, v1, vcc
	v_lshlrev_b32_e32 v171, 2, v0
	v_lshrrev_b32_e32 v0, 1, v144
	v_and_b32_e32 v126, 16, v0
	v_lshl_add_u64 v[0:1], s[62:63], 0, v[126:127]
	v_lshl_add_u64 v[148:149], v[0:1], 0, s[56:57]
	v_mul_u32_u24_e32 v0, 0x90, v124
	v_add3_u32 v0, v0, v18, 0
	v_add_u32_e32 v172, 0x1200, v0
	v_or_b32_e32 v0, v22, v141
	v_mul_u32_u24_e32 v21, 0x210, v124
	v_add_u32_e32 v0, 0, v0
	v_lshrrev_b32_e32 v128, 3, v144
	v_and_b32_e32 v136, 0xff, v144
	v_and_b32_e32 v4, 24, v4
	v_lshrrev_b32_e32 v145, 3, v193
	s_lshl_b32 s66, s3, 9
	s_add_i32 s67, 0, 0x22400
	v_add_u32_e32 v174, 0x9000, v0
	v_or_b32_e32 v0, v21, v141
	v_mul_u32_u24_e32 v5, 0x90, v128
	s_movk_i32 s0, 0x1ff
	v_mul_u32_u24_e32 v7, 0x90, v130
	v_mul_u32_u24_e32 v9, 0x90, v132
	v_mul_u32_u24_e32 v11, 0x90, v134
	s_movk_i32 s4, 0x7f
	v_lshl_add_u32 v13, v136, 1, 0
	v_mul_u32_u24_e32 v14, 0x210, v4
	v_mul_u32_u24_e32 v15, 0x210, v6
	v_mul_u32_u24_e32 v16, 0x210, v8
	v_mul_u32_u24_e32 v17, 0x210, v10
	v_mul_u32_u24_e32 v23, 0x110, v145
	s_movk_i32 s42, 0x80
	v_lshl_add_u32 v170, v144, 2, s67
	s_add_i32 s67, s67, s66
	v_add_u32_e32 v0, 0, v0
	v_mov_b32_e32 v125, v127
	v_cmp_lt_u32_e64 s[0:1], s0, v144
	v_mov_b32_e32 v131, v127
	v_mov_b32_e32 v133, v127
	v_mov_b32_e32 v135, v127
	v_cmp_lt_u32_e64 s[4:5], s4, v136
	v_mov_b32_e32 v137, v127
	v_add_u32_e32 v140, 0, v18
	v_cmp_gt_u32_e64 s[6:7], 32, v193
	v_cmp_gt_u32_e64 s[8:9], v129, v124
	v_cmp_lt_u32_e64 s[10:11], v129, v124
	v_or_b32_e32 v147, 8, v145
	v_or_b32_e32 v168, 16, v145
	v_or_b32_e32 v169, 24, v145
	v_cmp_gt_u32_e64 s[42:43], s42, v144
	v_lshl_add_u32 v173, v193, 2, s67
	v_add_u32_e32 v175, 0x9000, v0
	s_movk_i32 s95, 0x2400
	v_add_u32_e32 v176, v3, v7
	v_lshlrev_b32_e32 v150, 1, v2
	v_add_u32_e32 v177, v3, v9
	v_add_u32_e32 v178, v3, v11
	v_lshlrev_b32_e32 v152, 1, v4
	v_add_u32_e32 v179, v13, v14
	v_lshlrev_b32_e32 v154, 1, v6
	v_add_u32_e32 v180, v13, v15
	v_lshlrev_b32_e32 v156, 1, v8
	v_add_u32_e32 v181, v13, v16
	v_lshlrev_b32_e32 v158, 1, v10
	v_add_u32_e32 v182, v13, v17
	v_lshlrev_b32_e32 v160, 1, v12
	s_movk_i32 s96, 0x1000
	s_mov_b32 s97, 0xf149f2ca
	v_add_u32_e32 v183, v19, v141
	v_add_u32_e32 v183, v183, v141
	v_add_u32_e32 v184, v20, v23
	s_mov_b64 s[56:57], 0x48000
	v_lshlrev_b32_e32 v185, 2, v144
	v_add_u32_e32 v186, v3, v5
	v_mov_b32_e32 v194, v127
	v_mov_b32_e32 v195, v127
	v_mov_b32_e32 v196, v127
	v_mov_b32_e32 v197, v127
	v_mov_b32_e32 v187, 0x2400
	v_mov_b32_e32 v188, 0xf149f2ca
	s_mov_b32 s98, s2
	s_branch .LBB0_298

.LBB0_314:
	s_or_b64 exec, exec, s[74:75]
	s_add_u32 s100, s66, s84
	s_lshl_b32 s100, s100, 12
	s_add_u32 s100, s100, s62
	s_addc_u32 s101, s63, 0
	s_add_u32 s100, s100, s70
	s_addc_u32 s101, s101, s71
	s_add_u32 s100, s100, 0x4000000
	s_addc_u32 s101, s101, 0
	ds_write_b128 v183, v[0:3]
	ds_write_b128 v183, v[4:7] offset:32
	ds_write_b128 v183, v[8:11] offset:64
	ds_write2_b64 v183, v[12:13], v[32:33] offset0:12 offset1:13
	ds_write_b128 v183, v[14:17] offset:128
	ds_write_b128 v183, v[18:21] offset:160
	ds_write_b128 v183, v[22:25] offset:192
	ds_write_b128 v183, v[26:29] offset:224
	s_waitcnt lgkmcnt(0)
	ds_read_b128 v[0:3], v184
	ds_read_b128 v[4:7], v184 offset:16
	ds_read_b128 v[16:19], v184 offset:2176
	ds_read_b128 v[20:23], v184 offset:2192
	s_waitcnt vmcnt(3)
	s_waitcnt lgkmcnt(2)
	v_lshlrev_b32_e32 v12, 16, v116
	v_and_b32_e32 v13, 0xffff0000, v116
	v_pk_mul_f32 v[0:1], v[80:81], v[0:1]
	v_pk_mul_f32 v[0:1], v[0:1], v[12:13]
	v_cvt_pk_bf16_f32 v8, v0, v1
	v_lshlrev_b32_e32 v12, 16, v117
	v_and_b32_e32 v13, 0xffff0000, v117
	v_pk_mul_f32 v[2:3], v[82:83], v[2:3]
	v_pk_mul_f32 v[2:3], v[2:3], v[12:13]
	v_cvt_pk_bf16_f32 v9, v2, v3
	v_lshlrev_b32_e32 v12, 16, v118
	v_and_b32_e32 v13, 0xffff0000, v118
	v_pk_mul_f32 v[4:5], v[84:85], v[4:5]
	v_pk_mul_f32 v[4:5], v[4:5], v[12:13]
	v_cvt_pk_bf16_f32 v10, v4, v5
	v_lshlrev_b32_e32 v12, 16, v119
	v_and_b32_e32 v13, 0xffff0000, v119
	v_pk_mul_f32 v[6:7], v[86:87], v[6:7]
	v_pk_mul_f32 v[6:7], v[6:7], v[12:13]
	v_cvt_pk_bf16_f32 v11, v6, v7
	global_store_dwordx4 v235, v[8:11], s[100:101]
	ds_read_b128 v[0:3], v184 offset:4352
	ds_read_b128 v[4:7], v184 offset:4368
	s_waitcnt vmcnt(3)
	s_waitcnt lgkmcnt(2)
	v_lshlrev_b32_e32 v12, 16, v112
	v_and_b32_e32 v13, 0xffff0000, v112
	v_pk_mul_f32 v[16:17], v[80:81], v[16:17]
	v_pk_mul_f32 v[16:17], v[16:17], v[12:13]
	v_cvt_pk_bf16_f32 v24, v16, v17
	v_lshlrev_b32_e32 v12, 16, v113
	v_and_b32_e32 v13, 0xffff0000, v113
	v_pk_mul_f32 v[18:19], v[82:83], v[18:19]
	v_pk_mul_f32 v[18:19], v[18:19], v[12:13]
	v_cvt_pk_bf16_f32 v25, v18, v19
	v_lshlrev_b32_e32 v12, 16, v114
	v_and_b32_e32 v13, 0xffff0000, v114
	v_pk_mul_f32 v[20:21], v[84:85], v[20:21]
	v_pk_mul_f32 v[20:21], v[20:21], v[12:13]
	v_cvt_pk_bf16_f32 v26, v20, v21
	v_lshlrev_b32_e32 v12, 16, v115
	v_and_b32_e32 v13, 0xffff0000, v115
	v_pk_mul_f32 v[22:23], v[86:87], v[22:23]
	v_pk_mul_f32 v[22:23], v[22:23], v[12:13]
	v_cvt_pk_bf16_f32 v27, v22, v23
	global_store_dwordx4 v236, v[24:27], s[100:101]
	ds_read_b128 v[16:19], v184 offset:6528
	ds_read_b128 v[20:23], v184 offset:6544
	s_waitcnt vmcnt(3)
	s_waitcnt lgkmcnt(2)
	v_lshlrev_b32_e32 v12, 16, v108
	v_and_b32_e32 v13, 0xffff0000, v108
	v_pk_mul_f32 v[0:1], v[80:81], v[0:1]
	v_pk_mul_f32 v[0:1], v[0:1], v[12:13]
	v_cvt_pk_bf16_f32 v8, v0, v1
	v_lshlrev_b32_e32 v12, 16, v109
	v_and_b32_e32 v13, 0xffff0000, v109
	v_pk_mul_f32 v[2:3], v[82:83], v[2:3]
	v_pk_mul_f32 v[2:3], v[2:3], v[12:13]
	v_cvt_pk_bf16_f32 v9, v2, v3
	v_lshlrev_b32_e32 v12, 16, v110
	v_and_b32_e32 v13, 0xffff0000, v110
	v_pk_mul_f32 v[4:5], v[84:85], v[4:5]
	v_pk_mul_f32 v[4:5], v[4:5], v[12:13]
	v_cvt_pk_bf16_f32 v10, v4, v5
	v_lshlrev_b32_e32 v12, 16, v111
	v_and_b32_e32 v13, 0xffff0000, v111
	v_pk_mul_f32 v[6:7], v[86:87], v[6:7]
	v_pk_mul_f32 v[6:7], v[6:7], v[12:13]
	v_cvt_pk_bf16_f32 v11, v6, v7
	global_store_dwordx4 v237, v[8:11], s[100:101]
	s_waitcnt vmcnt(3)
	s_waitcnt lgkmcnt(0)
	v_lshlrev_b32_e32 v12, 16, v104
	v_and_b32_e32 v13, 0xffff0000, v104
	v_pk_mul_f32 v[16:17], v[80:81], v[16:17]
	v_pk_mul_f32 v[16:17], v[16:17], v[12:13]
	v_cvt_pk_bf16_f32 v24, v16, v17
	v_lshlrev_b32_e32 v12, 16, v105
	v_and_b32_e32 v13, 0xffff0000, v105
	v_pk_mul_f32 v[18:19], v[82:83], v[18:19]
	v_pk_mul_f32 v[18:19], v[18:19], v[12:13]
	v_cvt_pk_bf16_f32 v25, v18, v19
	v_lshlrev_b32_e32 v12, 16, v106
	v_and_b32_e32 v13, 0xffff0000, v106
	v_pk_mul_f32 v[20:21], v[84:85], v[20:21]
	v_pk_mul_f32 v[20:21], v[20:21], v[12:13]
	v_cvt_pk_bf16_f32 v26, v20, v21
	v_lshlrev_b32_e32 v12, 16, v107
	v_and_b32_e32 v13, 0xffff0000, v107
	v_pk_mul_f32 v[22:23], v[86:87], v[22:23]
	v_pk_mul_f32 v[22:23], v[22:23], v[12:13]
	v_cvt_pk_bf16_f32 v27, v22, v23
	global_store_dwordx4 v238, v[24:27], s[100:101]
	s_waitcnt lgkmcnt(0)
	s_add_i32 s76, s76, 32
	s_add_i32 s69, s69, 64
	s_add_i32 s77, s77, 1
	v_mov_b64_e32 v[48:49], v[88:89]
	v_mov_b64_e32 v[110:111], v[94:95]
	v_mov_b64_e32 v[106:107], v[98:99]
	v_mov_b64_e32 v[122:123], v[102:103]
	v_add_u32_e32 v153, 0x1200, v153
	v_lshl_add_u64 v[164:165], v[164:165], 0, s[56:57]
	v_add_u32_e32 v151, 0x80, v151
	s_cmpk_eq_i32 s69, 0x100
	v_mov_b64_e32 v[50:51], v[90:91]
	v_mov_b64_e32 v[108:109], v[92:93]
	v_mov_b64_e32 v[104:105], v[96:97]
	v_mov_b64_e32 v[120:121], v[100:101]
	s_cbranch_scc1 .LBB0_322
